# phase 2 scoring on v_mfma_f32_32x32x16_bf16 (16 MFMA issues per 64-key chunk instead of 32; same VALU work)
# speedup vs baseline: 1.0001x; 1.0001x over previous
; __device__ void phase2(const Params& p, unsigned char* smem) {
;     ...
;     const u16* QI = (const u16*)(ws + OFF_QI);
;     const float* WI = (const float*)(ws + OFF_WI);
;     const int n16 = lane & 15, g4 = lane >> 4;
;     bf16x8 qa[4][2]; float4 wv[4];
; #pragma unroll
;     for (int pp = 0; pp < 4; pp++) {
;       const int ql = 2 * pp + (n16 >> 3), hh = n16 & 7;
; #pragma unroll
;       for (int kh = 0; kh < 2; kh++)
;         qa[pp][kh] = as_bf8(*(const uint4*)(QI + (size_t)(tok0 + ql) * 512 + hh * 64 + kh * 32 + 8 * g4));
;       wv[pp] = *(const float4*)(WI + (size_t)(tok0 + 2 * pp + (g4 >> 1)) * 8 + 4 * (g4 & 1));
;     }
;     {
;       const int nchunk = nvis >> 6;
;       const u16* kbase = KI + (size_t)n16 * 64 + 8 * g4;
;       bf16x8 nA0, nB0, nA1, nB1, nA2, nB2, nA3, nB3;
;       int c = wave;
;       if (c < nchunk) P2_LOADCHUNK(c, nA0, nB0, nA1, nB1, nA2, nB2, nA3, nB3)
;       for (; c < nchunk; c += 8) {
;         bf16x8 cA0 = nA0, cB0 = nB0, cA1 = nA1, cB1 = nB1, cA2 = nA2, cB2 = nB2, cA3 = nA3, cB3 = nB3;
;         if (c + 8 < nchunk) P2_LOADCHUNK(c + 8, nA0, nB0, nA1, nB1, nA2, nB2, nA3, nB3)
;         __builtin_amdgcn_sched_barrier(0);
;         P2_SCORE(cA0, cB0, c * 4 + 0)
;         P2_SCORE(cA1, cB1, c * 4 + 1)
;         P2_SCORE(cA2, cB2, c * 4 + 2)
;         P2_SCORE(cA3, cB3, c * 4 + 3)
;       }
.LBB0_533:
	s_add_i32 s45, s74, 0x1ff
	s_and_b32 s36, s45, 0xfffffe00
	s_sub_i32 s76, s36, s74
	s_lshl_b32 s47, s76, 3
	s_lshr_b32 s73, s45, 9
	s_cmp_lg_u32 s97, 0
	s_cbranch_scc1 .Lq_skip
	s_add_u32 s36, s88, 0xa220800
	s_addc_u32 s37, s89, 0
	v_and_b32_e32 v70, 31, v154
	v_lshrrev_b32_e32 v70, 3, v70
	v_add_u32_e32 v70, s75, v70
	v_ashrrev_i32_e32 v71, 31, v70
	v_add_u32_e32 v74, 4, v70
	v_lshlrev_b64 v[72:73], 10, v[70:71]
	v_ashrrev_i32_e32 v75, 31, v74
	v_and_b32_e32 v76, 7, v154
	v_lshlrev_b64 v[74:75], 10, v[74:75]
	v_lshrrev_b32_e32 v78, 5, v154
	v_lshlrev_b32_e32 v76, 7, v76
	v_mov_b32_e32 v77, 0
	v_lshl_or_b32 v76, v78, 4, v76
	v_lshl_add_u64 v[72:73], v[72:73], 0, s[36:37]
	v_lshl_add_u64 v[74:75], v[74:75], 0, s[36:37]
	v_lshl_add_u64 v[72:73], v[72:73], 0, v[76:77]
	v_lshl_add_u64 v[74:75], v[74:75], 0, v[76:77]
	s_add_u32 s36, s88, 0x144a0800
	s_addc_u32 s37, s89, 0
	s_lshl_b32 s38, s75, 5
	v_lshlrev_b32_e32 v78, 4, v78
	v_mov_b32_e32 v79, 0
	v_add_u32_e32 v78, s38, v78
	v_lshl_add_u64 v[78:79], v[78:79], 0, s[36:37]
	global_load_dwordx4 v[38:41], v[72:73], off
	global_load_dwordx4 v[42:45], v[72:73], off offset:32
	global_load_dwordx4 v[46:49], v[72:73], off offset:64
	global_load_dwordx4 v[50:53], v[72:73], off offset:96
	global_load_dwordx4 v[54:57], v[74:75], off
	global_load_dwordx4 v[58:61], v[74:75], off offset:32
	global_load_dwordx4 v[62:65], v[74:75], off offset:64
	global_load_dwordx4 v[66:69], v[74:75], off offset:96
	global_load_dwordx4 v[86:89], v[78:79], off
	global_load_dwordx4 v[90:93], v[78:79], off offset:32
	global_load_dwordx4 v[94:97], v[78:79], off offset:64
	global_load_dwordx4 v[98:101], v[78:79], off offset:96
	global_load_dwordx4 v[102:105], v[78:79], off offset:128
	global_load_dwordx4 v[106:109], v[78:79], off offset:160
	global_load_dwordx4 v[110:113], v[78:79], off offset:192
	global_load_dwordx4 v[114:117], v[78:79], off offset:224
.Lq_skip:
	s_lshr_b32 s47, s74, 6
	v_cmp_gt_u32_e64 s[36:37], s47, v133
	s_and_saveexec_b64 s[38:39], s[36:37]
	s_cbranch_execz .LBB0_548
	v_and_b32_e32 v70, 31, v154
	v_lshrrev_b32_e32 v71, 5, v154
	v_lshlrev_b32_e32 v70, 7, v70
	v_lshl_or_b32 v70, v71, 4, v70
	v_lshl_or_b32 v70, v133, 13, v70
	v_mov_b32_e32 v71, 0
	v_lshl_add_u64 v[142:143], s[48:49], 0, v[70:71]
	global_load_dwordx4 v[6:9], v[142:143], off
	global_load_dwordx4 v[10:13], v[142:143], off offset:32
	global_load_dwordx4 v[14:17], v[142:143], off offset:64
	global_load_dwordx4 v[18:21], v[142:143], off offset:96
	v_add_co_u32_e32 v208, vcc, 0x1000, v142
	s_nop 1
	v_addc_co_u32_e32 v209, vcc, 0, v143, vcc
	global_load_dwordx4 v[22:25], v[208:209], off
	global_load_dwordx4 v[26:29], v[208:209], off offset:32
	global_load_dwordx4 v[30:33], v[208:209], off offset:64
	global_load_dwordx4 v[34:37], v[208:209], off offset:96
.LBB0_548:
	s_or_b64 exec, exec, s[38:39]
	s_and_saveexec_b64 s[38:39], s[36:37]
	s_cbranch_execz .LBB0_554
	s_waitcnt vmcnt(0)
	v_readfirstlane_b32 s40, v133
	v_lshl_add_u64 v[142:143], v[142:143], 0, s[60:61]
	v_lshl_add_u64 v[208:209], v[208:209], 0, s[60:61]
	v_lshrrev_b32_e32 v203, 5, v154
	v_and_b32_e32 v204, 31, v154
	v_lshlrev_b32_e32 v203, 14, v203
	v_lshl_or_b32 v210, v204, 1, v203
	v_lshl_add_u32 v210, v133, 7, v210
	s_add_i32 s41, s40, 8
	v_add_u32_e32 v211, 0x10000, v210
.Lsc_loop:
	s_cmp_lt_u32 s41, s47
	s_cselect_b64 vcc, 0, -1
	s_waitcnt vmcnt(4)
	v_mfma_f32_32x32x16_bf16 v[168:183], v[38:41], v[6:9], 0
	v_mfma_f32_32x32x16_bf16 v[168:183], v[42:45], v[10:13], v[168:183]
	v_mfma_f32_32x32x16_bf16 v[168:183], v[46:49], v[14:17], v[168:183]
	v_mfma_f32_32x32x16_bf16 v[168:183], v[50:53], v[18:21], v[168:183]
	v_mfma_f32_32x32x16_bf16 v[184:199], v[54:57], v[6:9], 0
	v_mfma_f32_32x32x16_bf16 v[184:199], v[58:61], v[10:13], v[184:199]
	v_mfma_f32_32x32x16_bf16 v[184:199], v[62:65], v[14:17], v[184:199]
	v_mfma_f32_32x32x16_bf16 v[184:199], v[66:69], v[18:21], v[184:199]
	s_cbranch_vccnz .Lsc_np0
	global_load_dwordx4 v[6:9], v[142:143], off
	global_load_dwordx4 v[10:13], v[142:143], off offset:32
	global_load_dwordx4 v[14:17], v[142:143], off offset:64
	global_load_dwordx4 v[18:21], v[142:143], off offset:96
	s_branch .Lsc_c0

; __device__ void phase2(const Params& p, unsigned char* smem) {
;     ...
;         P2_SCORE(cA0, cB0, c * 4 + 0)
;         P2_SCORE(cA1, cB1, c * 4 + 1)
;         P2_SCORE(cA2, cB2, c * 4 + 2)
;         P2_SCORE(cA3, cB3, c * 4 + 3)
.Lsc_c0:
	v_max_f32_e32 v169, 0, v169
	v_max_f32_e32 v168, 0, v168
	v_mul_f32_e32 v169, v87, v169
	v_max_f32_e32 v170, 0, v170
	v_fmac_f32_e32 v169, v86, v168
	v_max_f32_e32 v171, 0, v171
	v_fmac_f32_e32 v169, v88, v170
	v_fmac_f32_e32 v169, v89, v171
	v_max_f32_e32 v173, 0, v173
	v_max_f32_e32 v172, 0, v172
	v_mul_f32_e32 v173, v91, v173
	v_max_f32_e32 v174, 0, v174
	v_fmac_f32_e32 v173, v90, v172
	v_max_f32_e32 v175, 0, v175
	v_fmac_f32_e32 v173, v92, v174
	v_fmac_f32_e32 v173, v93, v175
	v_max_f32_e32 v177, 0, v177
	v_max_f32_e32 v176, 0, v176
	v_permlane32_swap_b32_e32 v169, v173
	v_add_f32_e32 v200, v169, v173
	v_cvt_f16_f32_e32 v200, v200
	v_bfe_i32 v202, v200, 15, 1
	v_bitop3_b16 v200, v202, v200, s71 bitop3:0x36
	ds_write_b16 v210, v200
	v_mul_f32_e32 v177, v95, v177
	v_max_f32_e32 v178, 0, v178
	v_fmac_f32_e32 v177, v94, v176
	v_max_f32_e32 v179, 0, v179
	v_fmac_f32_e32 v177, v96, v178
	v_fmac_f32_e32 v177, v97, v179
	v_max_f32_e32 v181, 0, v181
	v_max_f32_e32 v180, 0, v180
	v_mul_f32_e32 v181, v99, v181
	v_max_f32_e32 v182, 0, v182
	v_fmac_f32_e32 v181, v98, v180
	v_max_f32_e32 v183, 0, v183
	v_fmac_f32_e32 v181, v100, v182
	v_fmac_f32_e32 v181, v101, v183
	s_nop 1
	v_permlane32_swap_b32_e32 v177, v181
	v_add_f32_e32 v201, v177, v181
	v_cvt_f16_f32_e32 v201, v201
	v_bfe_i32 v202, v201, 15, 1
	v_bitop3_b16 v201, v202, v201, s71 bitop3:0x36
	ds_write_b16 v210, v201 offset:32768
	s_waitcnt vmcnt(4)
	v_mfma_f32_32x32x16_bf16 v[168:183], v[38:41], v[22:25], 0
	v_mfma_f32_32x32x16_bf16 v[168:183], v[42:45], v[26:29], v[168:183]
	v_mfma_f32_32x32x16_bf16 v[168:183], v[46:49], v[30:33], v[168:183]
	v_mfma_f32_32x32x16_bf16 v[168:183], v[50:53], v[34:37], v[168:183]
	v_max_f32_e32 v185, 0, v185
	v_max_f32_e32 v184, 0, v184
	v_mul_f32_e32 v185, v103, v185
	v_max_f32_e32 v186, 0, v186
	v_fmac_f32_e32 v185, v102, v184
	v_max_f32_e32 v187, 0, v187
	v_fmac_f32_e32 v185, v104, v186
	v_fmac_f32_e32 v185, v105, v187
	v_max_f32_e32 v189, 0, v189
	v_max_f32_e32 v188, 0, v188
	v_mul_f32_e32 v189, v107, v189
	v_max_f32_e32 v190, 0, v190
	v_fmac_f32_e32 v189, v106, v188
	v_max_f32_e32 v191, 0, v191
	v_fmac_f32_e32 v189, v108, v190
	v_fmac_f32_e32 v189, v109, v191
	v_max_f32_e32 v193, 0, v193
	v_max_f32_e32 v192, 0, v192
	v_permlane32_swap_b32_e32 v185, v189
	v_add_f32_e32 v200, v185, v189
	v_cvt_f16_f32_e32 v200, v200
	v_bfe_i32 v202, v200, 15, 1
	v_bitop3_b16 v200, v202, v200, s71 bitop3:0x36
	ds_write_b16 v211, v200
	v_mul_f32_e32 v193, v111, v193
	v_max_f32_e32 v194, 0, v194
	v_fmac_f32_e32 v193, v110, v192
	v_max_f32_e32 v195, 0, v195
	v_fmac_f32_e32 v193, v112, v194
	v_fmac_f32_e32 v193, v113, v195
	v_max_f32_e32 v197, 0, v197
	v_max_f32_e32 v196, 0, v196
	v_mul_f32_e32 v197, v115, v197
	v_max_f32_e32 v198, 0, v198
	v_fmac_f32_e32 v197, v114, v196
	v_max_f32_e32 v199, 0, v199
	v_fmac_f32_e32 v197, v116, v198
	v_fmac_f32_e32 v197, v117, v199
	s_nop 1
	v_permlane32_swap_b32_e32 v193, v197
	v_add_f32_e32 v201, v193, v197
	v_cvt_f16_f32_e32 v201, v201
	v_bfe_i32 v202, v201, 15, 1
	v_bitop3_b16 v201, v202, v201, s71 bitop3:0x36
	ds_write_b16 v211, v201 offset:32768
	v_mfma_f32_32x32x16_bf16 v[184:199], v[54:57], v[22:25], 0
	v_mfma_f32_32x32x16_bf16 v[184:199], v[58:61], v[26:29], v[184:199]
	v_mfma_f32_32x32x16_bf16 v[184:199], v[62:65], v[30:33], v[184:199]
	v_mfma_f32_32x32x16_bf16 v[184:199], v[66:69], v[34:37], v[184:199]
	s_cbranch_vccnz .Lsc_np1
	global_load_dwordx4 v[22:25], v[208:209], off
	global_load_dwordx4 v[26:29], v[208:209], off offset:32
	global_load_dwordx4 v[30:33], v[208:209], off offset:64
	global_load_dwordx4 v[34:37], v[208:209], off offset:96
	s_branch .Lsc_c1

; __device__ void phase2(const Params& p, unsigned char* smem) {
;     ...
;       for (; c < nchunk; c += 8) {
;         bf16x8 cA0 = nA0, cB0 = nB0, cA1 = nA1, cB1 = nB1, cA2 = nA2, cB2 = nB2, cA3 = nA3, cB3 = nB3;
;         if (c + 8 < nchunk) P2_LOADCHUNK(c + 8, nA0, nB0, nA1, nB1, nA2, nB2, nA3, nB3)
;         __builtin_amdgcn_sched_barrier(0);
;         P2_SCORE(cA0, cB0, c * 4 + 0)
;         P2_SCORE(cA1, cB1, c * 4 + 1)
;         P2_SCORE(cA2, cB2, c * 4 + 2)
;         P2_SCORE(cA3, cB3, c * 4 + 3)
;       }
.Lsc_c1:
	v_max_f32_e32 v169, 0, v169
	v_max_f32_e32 v168, 0, v168
	v_mul_f32_e32 v169, v87, v169
	v_max_f32_e32 v170, 0, v170
	v_fmac_f32_e32 v169, v86, v168
	v_max_f32_e32 v171, 0, v171
	v_fmac_f32_e32 v169, v88, v170
	v_fmac_f32_e32 v169, v89, v171
	v_max_f32_e32 v173, 0, v173
	v_max_f32_e32 v172, 0, v172
	v_mul_f32_e32 v173, v91, v173
	v_max_f32_e32 v174, 0, v174
	v_fmac_f32_e32 v173, v90, v172
	v_max_f32_e32 v175, 0, v175
	v_fmac_f32_e32 v173, v92, v174
	v_fmac_f32_e32 v173, v93, v175
	v_max_f32_e32 v177, 0, v177
	v_max_f32_e32 v176, 0, v176
	v_permlane32_swap_b32_e32 v169, v173
	v_add_f32_e32 v200, v169, v173
	v_cvt_f16_f32_e32 v200, v200
	v_bfe_i32 v202, v200, 15, 1
	v_bitop3_b16 v200, v202, v200, s71 bitop3:0x36
	ds_write_b16 v210, v200 offset:64
	v_mul_f32_e32 v177, v95, v177
	v_max_f32_e32 v178, 0, v178
	v_fmac_f32_e32 v177, v94, v176
	v_max_f32_e32 v179, 0, v179
	v_fmac_f32_e32 v177, v96, v178
	v_fmac_f32_e32 v177, v97, v179
	v_max_f32_e32 v181, 0, v181
	v_max_f32_e32 v180, 0, v180
	v_mul_f32_e32 v181, v99, v181
	v_max_f32_e32 v182, 0, v182
	v_fmac_f32_e32 v181, v98, v180
	v_max_f32_e32 v183, 0, v183
	v_fmac_f32_e32 v181, v100, v182
	v_fmac_f32_e32 v181, v101, v183
	s_nop 1
	v_permlane32_swap_b32_e32 v177, v181
	v_add_f32_e32 v201, v177, v181
	v_cvt_f16_f32_e32 v201, v201
	v_bfe_i32 v202, v201, 15, 1
	v_bitop3_b16 v201, v202, v201, s71 bitop3:0x36
	ds_write_b16 v210, v201 offset:32832
	v_max_f32_e32 v185, 0, v185
	v_max_f32_e32 v184, 0, v184
	v_mul_f32_e32 v185, v103, v185
	v_max_f32_e32 v186, 0, v186
	v_fmac_f32_e32 v185, v102, v184
	v_max_f32_e32 v187, 0, v187
	v_fmac_f32_e32 v185, v104, v186
	v_fmac_f32_e32 v185, v105, v187
	v_max_f32_e32 v189, 0, v189
	v_max_f32_e32 v188, 0, v188
	v_mul_f32_e32 v189, v107, v189
	v_max_f32_e32 v190, 0, v190
	v_fmac_f32_e32 v189, v106, v188
	v_max_f32_e32 v191, 0, v191
	v_fmac_f32_e32 v189, v108, v190
	v_fmac_f32_e32 v189, v109, v191
	v_max_f32_e32 v193, 0, v193
	v_max_f32_e32 v192, 0, v192
	v_permlane32_swap_b32_e32 v185, v189
	v_add_f32_e32 v200, v185, v189
	v_cvt_f16_f32_e32 v200, v200
	v_bfe_i32 v202, v200, 15, 1
	v_bitop3_b16 v200, v202, v200, s71 bitop3:0x36
	ds_write_b16 v211, v200 offset:64
	v_mul_f32_e32 v193, v111, v193
	v_max_f32_e32 v194, 0, v194
	v_fmac_f32_e32 v193, v110, v192
	v_max_f32_e32 v195, 0, v195
	v_fmac_f32_e32 v193, v112, v194
	v_fmac_f32_e32 v193, v113, v195
	v_max_f32_e32 v197, 0, v197
	v_max_f32_e32 v196, 0, v196
	v_mul_f32_e32 v197, v115, v197
	v_max_f32_e32 v198, 0, v198
	v_fmac_f32_e32 v197, v114, v196
	v_max_f32_e32 v199, 0, v199
	v_fmac_f32_e32 v197, v116, v198
	v_fmac_f32_e32 v197, v117, v199
	s_nop 1
	v_permlane32_swap_b32_e32 v193, v197
	v_add_f32_e32 v201, v193, v197
	v_cvt_f16_f32_e32 v201, v201
	v_bfe_i32 v202, v201, 15, 1
	v_bitop3_b16 v201, v202, v201, s71 bitop3:0x36
	ds_write_b16 v211, v201 offset:32832
	v_lshl_add_u64 v[142:143], v[142:143], 0, s[60:61]
	v_lshl_add_u64 v[208:209], v[208:209], 0, s[60:61]
	v_add_u32_e32 v210, 0x400, v210
	v_add_u32_e32 v211, 0x400, v211
	s_add_i32 s40, s40, 8
	s_add_i32 s41, s41, 8
	s_cmp_lt_u32 s40, s47
	s_cbranch_scc1 .Lsc_loop

; __device__ void phase2(const Params& p, unsigned char* smem) {
;     ...
;     bf16x8 qa[4][2]; float4 wv[4];
; #pragma unroll
;     for (int pp = 0; pp < 4; pp++) {
;       const int ql = 2 * pp + (n16 >> 3), hh = n16 & 7;
; #pragma unroll
;       for (int kh = 0; kh < 2; kh++)
;         qa[pp][kh] = as_bf8(*(const uint4*)(QI + (size_t)(tok0 + ql) * 512 + hh * 64 + kh * 32 + 8 * g4));
;       wv[pp] = *(const float4*)(WI + (size_t)(tok0 + 2 * pp + (g4 >> 1)) * 8 + 4 * (g4 & 1));
;     }
.Lq_issue:
	s_add_u32 s36, s88, 0xa220800
	s_addc_u32 s37, s89, 0
	v_and_b32_e32 v70, 31, v154
	v_lshrrev_b32_e32 v70, 3, v70
	v_add_u32_e32 v70, s95, v70
	v_ashrrev_i32_e32 v71, 31, v70
	v_add_u32_e32 v74, 4, v70
	v_lshlrev_b64 v[72:73], 10, v[70:71]
	v_ashrrev_i32_e32 v75, 31, v74
	v_and_b32_e32 v76, 7, v154
	v_lshlrev_b64 v[74:75], 10, v[74:75]
	v_lshrrev_b32_e32 v78, 5, v154
	v_lshlrev_b32_e32 v76, 7, v76
	v_mov_b32_e32 v77, 0
	v_lshl_or_b32 v76, v78, 4, v76
	v_lshl_add_u64 v[72:73], v[72:73], 0, s[36:37]
	v_lshl_add_u64 v[74:75], v[74:75], 0, s[36:37]
	v_lshl_add_u64 v[72:73], v[72:73], 0, v[76:77]
	v_lshl_add_u64 v[74:75], v[74:75], 0, v[76:77]
	s_add_u32 s36, s88, 0x144a0800
	s_addc_u32 s37, s89, 0
	s_lshl_b32 s38, s95, 5
	v_lshlrev_b32_e32 v78, 4, v78
	v_mov_b32_e32 v79, 0
	v_add_u32_e32 v78, s38, v78
	v_lshl_add_u64 v[78:79], v[78:79], 0, s[36:37]
	global_load_dwordx4 v[38:41], v[72:73], off
	global_load_dwordx4 v[42:45], v[72:73], off offset:32
	global_load_dwordx4 v[46:49], v[72:73], off offset:64
	global_load_dwordx4 v[50:53], v[72:73], off offset:96
	global_load_dwordx4 v[54:57], v[74:75], off
	global_load_dwordx4 v[58:61], v[74:75], off offset:32
	global_load_dwordx4 v[62:65], v[74:75], off offset:64
	global_load_dwordx4 v[66:69], v[74:75], off offset:96
	global_load_dwordx4 v[86:89], v[78:79], off
	global_load_dwordx4 v[90:93], v[78:79], off offset:32
	global_load_dwordx4 v[94:97], v[78:79], off offset:64
	global_load_dwordx4 v[98:101], v[78:79], off offset:96
	global_load_dwordx4 v[102:105], v[78:79], off offset:128
	global_load_dwordx4 v[106:109], v[78:79], off offset:160
	global_load_dwordx4 v[110:113], v[78:79], off offset:192
	global_load_dwordx4 v[114:117], v[78:79], off offset:224
	s_mov_b32 s97, 1
